# final candidate re-measure: peel P2/P7 + DPP reductions + attention bias interleave + P2 stores sc0 sc1 nt + DMA-before-ds_read
# baseline (speedup 1.0000x reference)
; #define PG8_STAGE(bufoff, gbase, voff) do { _Pragma("unroll") for (int _i = 0; _i < 2; ++_i) \
;         __builtin_amdgcn_global_load_lds((const unsigned*)((const char*)(gbase) + (voff)[_i]), (PG8_LAS unsigned*)(lds + (bufoff) + ldsw + _i * 8192), 16, 0, 0); } while (0)
; #define PG8_LDA(dst, b, h) do { _Pragma("unroll") for (int m = 0; m < 4; ++m) _Pragma("unroll") for (int k = 0; k < 2; ++k) dst[m][k] = *(const PG8_LAS bf16x8*)(lds + PG8_SA(b, h) + aoff + m * 2048 + k * 1024); } while (0)
; #define PG8_LDB(dst, b, h) do { _Pragma("unroll") for (int n = 0; n < 2; ++n) _Pragma("unroll") for (int k = 0; k < 2; ++k) dst[n][k] = *(const PG8_LAS bf16x8*)(lds + PG8_SB(b, h) + boff + n * 2048 + k * 1024); } while (0)
; #define PG8_SCHED __builtin_amdgcn_sched_barrier(0)
; template <class Epi, class Sched, bool ALIGN_EPI = false, bool SP2 = false>
; __device__ __forceinline__ void gemm_phase(PG8_LAS unsigned char* lds, const Gemm g, const Sched& S, const Epi& E) {
;     ...
;         const char* nA = has_next ? (const char*)g.A + (size_t)nxt.pm * tstepA + (size_t)nxt.pn * apn : cA; const char* nB = has_next ? (const char*)g.Bt + (size_t)nxt.pn * tstepB : cB;
;         for (int t = 0; t < nt; t += 2) {
;             const bool last = (t == nt - 2);
;             const char* a1 = cA + (size_t)(t + 1) * kstep;
;             const char* a2 = last ? nA : cA + (size_t)(t + 2) * kstep; const char* b2 = last ? nB : cB + (size_t)(t + 2) * kstep;
;             const char* a3 = a2 + kstep; const char* b3 = b2 + kstep;
;             if (last && has_next) S.a_ready(nxt);
;             if constexpr (SP2) {
;             PG8_LDB(B0, 0, 0); PG8_LDB(B1, 0, 1); PG8_SCHED; PG8_LDA(At, 0, 0); PG8_STAGE(PG8_SA(1, 1), a1 + hstepA, voffA);
;     ...
;         for (int a = 0; a < 2; ++a)
; #pragma unroll
;             for (int b = 0; b < 2; ++b)
; #pragma unroll
;                 for (int m = 0; m < 4; ++m)
; #pragma unroll
;                     for (int n = 0; n < 2; ++n) acc[a][b][m][n] = (f32x4){0.f, 0.f, 0.f, 0.f};
.LBB0_196:
	s_ashr_i32 s15, s14, 31
	s_lshl_b64 s[16:17], s[14:15], 19
	s_add_u32 s16, s24, s16
	s_addc_u32 s17, s25, s17
	s_and_b64 s[56:57], s[4:5], exec
	s_cselect_b32 s15, s17, s61
	s_cselect_b32 vcc_lo, s16, s60
	s_ashr_i32 s13, s12, 31
	s_lshl_b64 s[56:57], s[12:13], 19
	s_add_u32 s56, s82, s56
	s_addc_u32 s57, s83, s57
	s_and_b64 s[74:75], s[4:5], exec
	s_cselect_b32 s13, s57, s67
	s_cselect_b32 vcc_hi, s56, s66
	s_add_u32 s60, s60, 0x40080
	s_addc_u32 s61, s61, 0
	s_add_u32 s80, s66, 0x100
	v_mov_b32_e32 v0, 0
	s_addc_u32 s81, s67, 0
	s_mov_b32 s74, -2
	v_mov_b32_e32 v1, v0
	v_mov_b32_e32 v2, v0
	v_mov_b32_e32 v3, v0
	v_mov_b32_e32 v4, v0
	v_mov_b32_e32 v5, v0
	v_mov_b32_e32 v6, v0
	v_mov_b32_e32 v7, v0
	v_mov_b32_e32 v8, v0
	v_mov_b32_e32 v9, v0
	v_mov_b32_e32 v10, v0
	v_mov_b32_e32 v11, v0
	v_mov_b32_e32 v12, v0
	v_mov_b32_e32 v13, v0
	v_mov_b32_e32 v14, v0
	v_mov_b32_e32 v15, v0
	v_mov_b32_e32 v16, v0
	v_mov_b32_e32 v17, v0
	v_mov_b32_e32 v18, v0
	v_mov_b32_e32 v19, v0
	v_mov_b32_e32 v20, v0
	v_mov_b32_e32 v21, v0
	v_mov_b32_e32 v22, v0
	v_mov_b32_e32 v23, v0
	v_mov_b32_e32 v24, v0
	v_mov_b32_e32 v25, v0
	v_mov_b32_e32 v26, v0
	v_mov_b32_e32 v27, v0
	v_mov_b32_e32 v28, v0
	v_mov_b32_e32 v29, v0
	v_mov_b32_e32 v30, v0
	v_mov_b32_e32 v31, v0
	v_mov_b32_e32 v52, v0
	v_mov_b32_e32 v53, v0
	v_mov_b32_e32 v54, v0
	v_mov_b32_e32 v55, v0
	v_mov_b32_e32 v60, v0
	v_mov_b32_e32 v61, v0
	v_mov_b32_e32 v62, v0
	v_mov_b32_e32 v63, v0
	v_mov_b32_e32 v72, v0
	v_mov_b32_e32 v73, v0
	v_mov_b32_e32 v74, v0
	v_mov_b32_e32 v75, v0
	v_mov_b32_e32 v76, v0
	v_mov_b32_e32 v77, v0
	v_mov_b32_e32 v78, v0
	v_mov_b32_e32 v79, v0
	v_mov_b32_e32 v80, v0
	v_mov_b32_e32 v81, v0
	v_mov_b32_e32 v82, v0
	v_mov_b32_e32 v83, v0
	v_mov_b32_e32 v84, v0
	v_mov_b32_e32 v85, v0
	v_mov_b32_e32 v86, v0
	v_mov_b32_e32 v87, v0
	v_mov_b32_e32 v88, v0
	v_mov_b32_e32 v89, v0
	v_mov_b32_e32 v90, v0
	v_mov_b32_e32 v91, v0
	v_mov_b32_e32 v92, v0
	v_mov_b32_e32 v93, v0
	v_mov_b32_e32 v94, v0
	v_mov_b32_e32 v95, v0
	v_mov_b32_e32 v32, v0
	v_mov_b32_e32 v33, v0
	v_mov_b32_e32 v34, v0
	v_mov_b32_e32 v35, v0
	v_mov_b32_e32 v36, v0
	v_mov_b32_e32 v37, v0
	v_mov_b32_e32 v38, v0
	v_mov_b32_e32 v39, v0
	v_mov_b32_e32 v40, v0
	v_mov_b32_e32 v41, v0
	v_mov_b32_e32 v42, v0
	v_mov_b32_e32 v43, v0
	v_mov_b32_e32 v44, v0
	v_mov_b32_e32 v45, v0
	v_mov_b32_e32 v46, v0
	v_mov_b32_e32 v47, v0
	v_mov_b32_e32 v48, v0
	v_mov_b32_e32 v49, v0
	v_mov_b32_e32 v50, v0
	v_mov_b32_e32 v51, v0
	v_mov_b32_e32 v56, v0
	v_mov_b32_e32 v57, v0
	v_mov_b32_e32 v58, v0
	v_mov_b32_e32 v59, v0
	v_mov_b32_e32 v64, v0
	v_mov_b32_e32 v65, v0
	v_mov_b32_e32 v66, v0
	v_mov_b32_e32 v67, v0
	v_mov_b32_e32 v68, v0
	v_mov_b32_e32 v69, v0
	v_mov_b32_e32 v70, v0
	v_mov_b32_e32 v71, v0
	v_mov_b32_e32 v96, v0
	v_mov_b32_e32 v97, v0
	v_mov_b32_e32 v98, v0
	v_mov_b32_e32 v99, v0
	v_mov_b32_e32 v100, v0
	v_mov_b32_e32 v101, v0
	v_mov_b32_e32 v102, v0
	v_mov_b32_e32 v103, v0
	v_mov_b32_e32 v104, v0
	v_mov_b32_e32 v105, v0
	v_mov_b32_e32 v106, v0
	v_mov_b32_e32 v107, v0
	v_mov_b32_e32 v108, v0
	v_mov_b32_e32 v109, v0
	v_mov_b32_e32 v110, v0
	v_mov_b32_e32 v111, v0
	v_mov_b32_e32 v112, v0
	v_mov_b32_e32 v113, v0
	v_mov_b32_e32 v114, v0
	v_mov_b32_e32 v115, v0
	v_mov_b32_e32 v116, v0
	v_mov_b32_e32 v117, v0
	v_mov_b32_e32 v118, v0
	v_mov_b32_e32 v119, v0
	v_mov_b32_e32 v120, v0
	v_mov_b32_e32 v121, v0
	v_mov_b32_e32 v122, v0
	v_mov_b32_e32 v123, v0
	v_mov_b32_e32 v124, v0
	v_mov_b32_e32 v125, v0
	v_mov_b32_e32 v126, v0
	v_mov_b32_e32 v127, v0
	v_writelane_b32 v237, s60, 0
	v_writelane_b32 v237, s61, 1
	v_writelane_b32 v237, s66, 2
	v_writelane_b32 v237, s67, 3
	v_writelane_b32 v237, s15, 4
	v_writelane_b32 v237, vcc_lo, 5
	v_writelane_b32 v237, s13, 6
	v_writelane_b32 v237, vcc_hi, 7
	v_writelane_b32 v237, s80, 8
	v_writelane_b32 v237, s81, 9
	s_sub_u32 vcc_lo, s60, 0x40080
	s_subb_u32 s15, s61, 0
	s_mov_b32 vcc_hi, s66
	s_mov_b32 s13, s67
.Lcopy_loop:
	s_waitcnt lgkmcnt(0)
	ds_read_b128 v[146:149], v159
	ds_read_b128 v[162:165], v159 offset:1024
	ds_read_b128 v[166:169], v159 offset:2048
	ds_read_b128 v[170:173], v159 offset:3072
	ds_read_b128 v[176:179], v160
	ds_read_b128 v[180:183], v160 offset:1024
	ds_read_b128 v[184:187], v160 offset:2048
	ds_read_b128 v[188:191], v160 offset:3072
	s_add_u32 s66, s60, 0xfffc0080
	s_addc_u32 s67, s61, -1
	s_cmp_eq_u32 s74, 12
	s_cselect_b32 s85, s15, s67
	s_cselect_b32 s84, vcc_lo, s66
	s_cselect_b32 s67, s13, s81
	s_cselect_b32 s66, vcc_hi, s80
	v_lshl_add_u64 v[224:225], s[60:61], 0, v[138:139]
	s_add_i32 m0, s59, 0xc000
	ds_read_b128 v[192:195], v161
	ds_read_b128 v[196:199], v161 offset:1024
	ds_read_b128 v[200:203], v161 offset:2048
	ds_read_b128 v[204:207], v161 offset:3072
	ds_read_b128 v[208:211], v161 offset:4096
	ds_read_b128 v[212:215], v161 offset:5120
	ds_read_b128 v[216:219], v161 offset:6144
	ds_read_b128 v[220:223], v161 offset:7168
	global_load_lds_dwordx4 v[224:225], off
	v_lshl_add_u64 v[224:225], s[60:61], 0, v[140:141]
	s_add_i32 m0, s59, 0xe000
	s_nop 0
	global_load_lds_dwordx4 v[224:225], off
	s_waitcnt vmcnt(8)
	s_waitcnt lgkmcnt(0)
	s_barrier
; #define PG8_STAGE(bufoff, gbase, voff) do { _Pragma("unroll") for (int _i = 0; _i < 2; ++_i) \
;         __builtin_amdgcn_global_load_lds((const unsigned*)((const char*)(gbase) + (voff)[_i]), (PG8_LAS unsigned*)(lds + (bufoff) + ldsw + _i * 8192), 16, 0, 0); } while (0)
; #define PG8_LDA(dst, b, h) do { _Pragma("unroll") for (int m = 0; m < 4; ++m) _Pragma("unroll") for (int k = 0; k < 2; ++k) dst[m][k] = *(const PG8_LAS bf16x8*)(lds + PG8_SA(b, h) + aoff + m * 2048 + k * 1024); } while (0)
; #define PG8_LDB(dst, b, h) do { _Pragma("unroll") for (int n = 0; n < 2; ++n) _Pragma("unroll") for (int k = 0; k < 2; ++k) dst[n][k] = *(const PG8_LAS bf16x8*)(lds + PG8_SB(b, h) + boff + n * 2048 + k * 1024); } while (0)
; #define PG8_MMA(ai, bj, At, Bt) do { __builtin_amdgcn_s_setprio(1); _Pragma("unroll") for (int m = 0; m < 4; ++m) _Pragma("unroll") for (int n = 0; n < 2; ++n) _Pragma("unroll") for (int k = 0; k < 2; ++k) \
;         acc[ai][bj][m][n] = __builtin_amdgcn_mfma_f32_16x16x32_bf16(Bt[n][k], At[m][k], acc[ai][bj][m][n], 0, 0, 0); __builtin_amdgcn_s_setprio(0); } while (0)
; #define PG8_WAIT_V(n) asm volatile("s_waitcnt vmcnt(" #n ")" ::: "memory")
; #define PG8_WAIT_L(n) asm volatile("s_waitcnt lgkmcnt(" #n ")" ::: "memory")
; #define PG8_BAR __builtin_amdgcn_s_barrier()
; #define PG8_SCHED __builtin_amdgcn_sched_barrier(0)
; template <class Epi, class Sched, bool ALIGN_EPI = false, bool SP2 = false>
; __device__ __forceinline__ void gemm_phase(PG8_LAS unsigned char* lds, const Gemm g, const Sched& S, const Epi& E) {
;     ...
;             PG8_LDB(B0, 0, 0); PG8_LDB(B1, 0, 1); PG8_SCHED; PG8_LDA(At, 0, 0); PG8_STAGE(PG8_SA(1, 1), a1 + hstepA, voffA);
;             PG8_WAIT_V(8); PG8_WAIT_L(0); PG8_BAR; PG8_MMA(0, 0, At, B0); PG8_MMA(0, 1, At, B1); PG8_BAR; PG8_SCHED;
;             PG8_LDA(At, 0, 1); PG8_STAGE(PG8_SB(0, 0), b2, voffB); PG8_STAGE(PG8_SB(0, 1), b2 + hstepB, voffB); PG8_STAGE(PG8_SA(0, 0), a2, voffA);
;             PG8_WAIT_V(8); PG8_WAIT_L(0); PG8_BAR; PG8_MMA(1, 0, At, B0); PG8_MMA(1, 1, At, B1); PG8_BAR; PG8_SCHED;
	s_setprio 1
	s_waitcnt lgkmcnt(0)
	v_mfma_f32_16x16x32_bf16 v[124:127], v[146:149], v[192:195], v[124:127]
	v_mfma_f32_16x16x32_bf16 v[120:123], v[166:169], v[192:195], v[120:123]
	v_mfma_f32_16x16x32_bf16 v[116:119], v[146:149], v[200:203], v[116:119]
	v_mfma_f32_16x16x32_bf16 v[112:115], v[166:169], v[200:203], v[112:115]
	v_mfma_f32_16x16x32_bf16 v[108:111], v[146:149], v[208:211], v[108:111]
	v_mfma_f32_16x16x32_bf16 v[104:107], v[166:169], v[208:211], v[104:107]
	v_mfma_f32_16x16x32_bf16 v[100:103], v[146:149], v[216:219], v[100:103]
	v_mfma_f32_16x16x32_bf16 v[96:99], v[166:169], v[216:219], v[96:99]
	v_mfma_f32_16x16x32_bf16 v[124:127], v[162:165], v[196:199], v[124:127]
	v_mfma_f32_16x16x32_bf16 v[120:123], v[170:173], v[196:199], v[120:123]
	v_mfma_f32_16x16x32_bf16 v[116:119], v[162:165], v[204:207], v[116:119]
	v_mfma_f32_16x16x32_bf16 v[112:115], v[170:173], v[204:207], v[112:115]
	v_mfma_f32_16x16x32_bf16 v[108:111], v[162:165], v[212:215], v[108:111]
	v_mfma_f32_16x16x32_bf16 v[104:107], v[170:173], v[212:215], v[104:107]
	v_mfma_f32_16x16x32_bf16 v[100:103], v[162:165], v[220:223], v[100:103]
	v_mfma_f32_16x16x32_bf16 v[96:99], v[170:173], v[220:223], v[96:99]
	s_setprio 0
	s_setprio 1
	v_mfma_f32_16x16x32_bf16 v[68:71], v[176:179], v[192:195], v[68:71]
	v_mfma_f32_16x16x32_bf16 v[64:67], v[184:187], v[192:195], v[64:67]
	v_mfma_f32_16x16x32_bf16 v[56:59], v[176:179], v[200:203], v[56:59]
	v_mfma_f32_16x16x32_bf16 v[48:51], v[184:187], v[200:203], v[48:51]
	v_mfma_f32_16x16x32_bf16 v[44:47], v[176:179], v[208:211], v[44:47]
	v_mfma_f32_16x16x32_bf16 v[40:43], v[184:187], v[208:211], v[40:43]
	v_mfma_f32_16x16x32_bf16 v[36:39], v[176:179], v[216:219], v[36:39]
	v_mfma_f32_16x16x32_bf16 v[32:35], v[184:187], v[216:219], v[32:35]
	v_mfma_f32_16x16x32_bf16 v[68:71], v[180:183], v[196:199], v[68:71]
	v_mfma_f32_16x16x32_bf16 v[64:67], v[188:191], v[196:199], v[64:67]
	v_mfma_f32_16x16x32_bf16 v[56:59], v[180:183], v[204:207], v[56:59]
	v_mfma_f32_16x16x32_bf16 v[48:51], v[188:191], v[204:207], v[48:51]
	v_mfma_f32_16x16x32_bf16 v[44:47], v[180:183], v[212:215], v[44:47]
	v_mfma_f32_16x16x32_bf16 v[40:43], v[188:191], v[212:215], v[40:43]
	v_mfma_f32_16x16x32_bf16 v[36:39], v[180:183], v[220:223], v[36:39]
	v_mfma_f32_16x16x32_bf16 v[32:35], v[188:191], v[220:223], v[32:35]
	s_setprio 0
	s_add_i32 s75, s38, s27
	v_lshl_add_u64 v[224:225], s[66:67], 0, v[132:133]
	s_mov_b32 m0, s75
	ds_read_b128 v[192:195], v161 offset:16384
	ds_read_b128 v[196:199], v161 offset:17408
	ds_read_b128 v[200:203], v161 offset:18432
	ds_read_b128 v[204:207], v161 offset:19456
	ds_read_b128 v[208:211], v161 offset:20480
	ds_read_b128 v[212:215], v161 offset:21504
	ds_read_b128 v[216:219], v161 offset:22528
	ds_read_b128 v[220:223], v161 offset:23552
	global_load_lds_dwordx4 v[224:225], off
	s_add_i32 m0, s75, 0x2000
	s_add_u32 s76, s66, 0x40000
	v_lshl_add_u64 v[226:227], s[66:67], 0, v[128:129]
	s_addc_u32 s77, s67, 0
	s_add_i32 s75, s39, s27
	global_load_lds_dwordx4 v[226:227], off
	v_lshl_add_u64 v[228:229], s[76:77], 0, v[132:133]
	s_mov_b32 m0, s75
	v_lshl_add_u64 v[230:231], s[84:85], 0, v[130:131]
	global_load_lds_dwordx4 v[228:229], off
	v_lshl_add_u64 v[228:229], s[76:77], 0, v[128:129]
	s_add_i32 m0, s75, 0x2000
	s_nop 0
	global_load_lds_dwordx4 v[228:229], off
	v_lshl_add_u64 v[228:229], s[84:85], 0, v[134:135]
	s_mov_b32 m0, s59
	s_nop 0
	global_load_lds_dwordx4 v[228:229], off
	s_mov_b32 m0, s86
	s_nop 0
	global_load_lds_dwordx4 v[230:231], off
	s_waitcnt vmcnt(8)
	s_waitcnt lgkmcnt(0)
	s_barrier
	s_setprio 1
	s_waitcnt lgkmcnt(0)
	v_mfma_f32_16x16x32_bf16 v[92:95], v[146:149], v[192:195], v[92:95]
	v_mfma_f32_16x16x32_bf16 v[88:91], v[166:169], v[192:195], v[88:91]
	v_mfma_f32_16x16x32_bf16 v[84:87], v[146:149], v[200:203], v[84:87]
	v_mfma_f32_16x16x32_bf16 v[80:83], v[166:169], v[200:203], v[80:83]
	v_mfma_f32_16x16x32_bf16 v[76:79], v[146:149], v[208:211], v[76:79]
	v_mfma_f32_16x16x32_bf16 v[72:75], v[166:169], v[208:211], v[72:75]
	v_mfma_f32_16x16x32_bf16 v[60:63], v[146:149], v[216:219], v[60:63]
	v_mfma_f32_16x16x32_bf16 v[52:55], v[166:169], v[216:219], v[52:55]
	v_mfma_f32_16x16x32_bf16 v[92:95], v[162:165], v[196:199], v[92:95]
	v_mfma_f32_16x16x32_bf16 v[88:91], v[170:173], v[196:199], v[88:91]
	v_mfma_f32_16x16x32_bf16 v[84:87], v[162:165], v[204:207], v[84:87]
	v_mfma_f32_16x16x32_bf16 v[80:83], v[170:173], v[204:207], v[80:83]
	v_mfma_f32_16x16x32_bf16 v[76:79], v[162:165], v[212:215], v[76:79]
	v_mfma_f32_16x16x32_bf16 v[72:75], v[170:173], v[212:215], v[72:75]
	v_mfma_f32_16x16x32_bf16 v[60:63], v[162:165], v[220:223], v[60:63]
	v_mfma_f32_16x16x32_bf16 v[52:55], v[170:173], v[220:223], v[52:55]
	s_setprio 0
	s_setprio 1
	v_mfma_f32_16x16x32_bf16 v[28:31], v[176:179], v[192:195], v[28:31]
	v_mfma_f32_16x16x32_bf16 v[24:27], v[184:187], v[192:195], v[24:27]
	v_mfma_f32_16x16x32_bf16 v[20:23], v[176:179], v[200:203], v[20:23]
	v_mfma_f32_16x16x32_bf16 v[16:19], v[184:187], v[200:203], v[16:19]
	v_mfma_f32_16x16x32_bf16 v[12:15], v[176:179], v[208:211], v[12:15]
	v_mfma_f32_16x16x32_bf16 v[8:11], v[184:187], v[208:211], v[8:11]
	v_mfma_f32_16x16x32_bf16 v[4:7], v[176:179], v[216:219], v[4:7]
	v_mfma_f32_16x16x32_bf16 v[0:3], v[184:187], v[216:219], v[0:3]
	v_mfma_f32_16x16x32_bf16 v[28:31], v[180:183], v[196:199], v[28:31]
	v_mfma_f32_16x16x32_bf16 v[24:27], v[188:191], v[196:199], v[24:27]
	v_mfma_f32_16x16x32_bf16 v[20:23], v[180:183], v[204:207], v[20:23]
	v_mfma_f32_16x16x32_bf16 v[16:19], v[188:191], v[204:207], v[16:19]
	v_mfma_f32_16x16x32_bf16 v[12:15], v[180:183], v[212:215], v[12:15]
	v_mfma_f32_16x16x32_bf16 v[8:11], v[188:191], v[212:215], v[8:11]
	v_mfma_f32_16x16x32_bf16 v[4:7], v[180:183], v[220:223], v[4:7]
	v_mfma_f32_16x16x32_bf16 v[0:3], v[188:191], v[220:223], v[0:3]
	s_setprio 0
	s_add_i32 s75, 0, 0x18000
	s_add_i32 s33, 0, 0x1c000
	v_add_u32_e32 v170, s75, v151
	v_add_u32_e32 v175, s33, v151
	ds_read_b128 v[146:149], v170
	ds_read_b128 v[162:165], v170 offset:1024
	ds_read_b128 v[166:169], v170 offset:2048
	ds_read_b128 v[170:173], v170 offset:3072
	ds_read_b128 v[176:179], v175
	ds_read_b128 v[180:183], v175 offset:1024
	ds_read_b128 v[184:187], v175 offset:2048
	ds_read_b128 v[188:191], v175 offset:3072
	s_add_u32 s76, s84, 0x40000
	s_addc_u32 s77, s85, 0
	s_mov_b32 m0, s87
	v_lshl_add_u64 v[232:233], s[76:77], 0, v[134:135]
	ds_read_b128 v[192:195], v161 offset:32768
	ds_read_b128 v[196:199], v161 offset:33792
	ds_read_b128 v[200:203], v161 offset:34816
	ds_read_b128 v[204:207], v161 offset:35840
	ds_read_b128 v[208:211], v161 offset:36864
	ds_read_b128 v[212:215], v161 offset:37888
	ds_read_b128 v[216:219], v161 offset:38912
	ds_read_b128 v[220:223], v161 offset:39936
	global_load_lds_dwordx4 v[232:233], off
	v_lshl_add_u64 v[232:233], s[76:77], 0, v[130:131]
	s_mov_b32 m0, s88
	s_nop 0
	global_load_lds_dwordx4 v[232:233], off
	s_waitcnt vmcnt(8)
	s_waitcnt lgkmcnt(0)
	s_barrier
; #define PG8_STAGE(bufoff, gbase, voff) do { _Pragma("unroll") for (int _i = 0; _i < 2; ++_i) \
;         __builtin_amdgcn_global_load_lds((const unsigned*)((const char*)(gbase) + (voff)[_i]), (PG8_LAS unsigned*)(lds + (bufoff) + ldsw + _i * 8192), 16, 0, 0); } while (0)
; #define PG8_LDA(dst, b, h) do { _Pragma("unroll") for (int m = 0; m < 4; ++m) _Pragma("unroll") for (int k = 0; k < 2; ++k) dst[m][k] = *(const PG8_LAS bf16x8*)(lds + PG8_SA(b, h) + aoff + m * 2048 + k * 1024); } while (0)
; #define PG8_LDB(dst, b, h) do { _Pragma("unroll") for (int n = 0; n < 2; ++n) _Pragma("unroll") for (int k = 0; k < 2; ++k) dst[n][k] = *(const PG8_LAS bf16x8*)(lds + PG8_SB(b, h) + boff + n * 2048 + k * 1024); } while (0)
; #define PG8_MMA(ai, bj, At, Bt) do { __builtin_amdgcn_s_setprio(1); _Pragma("unroll") for (int m = 0; m < 4; ++m) _Pragma("unroll") for (int n = 0; n < 2; ++n) _Pragma("unroll") for (int k = 0; k < 2; ++k) \
;         acc[ai][bj][m][n] = __builtin_amdgcn_mfma_f32_16x16x32_bf16(Bt[n][k], At[m][k], acc[ai][bj][m][n], 0, 0, 0); __builtin_amdgcn_s_setprio(0); } while (0)
; #define PG8_WAIT_V(n) asm volatile("s_waitcnt vmcnt(" #n ")" ::: "memory")
; #define PG8_WAIT_L(n) asm volatile("s_waitcnt lgkmcnt(" #n ")" ::: "memory")
; #define PG8_BAR __builtin_amdgcn_s_barrier()
; #define PG8_SCHED __builtin_amdgcn_sched_barrier(0)
; template <class Epi, class Sched, bool ALIGN_EPI = false, bool SP2 = false>
; __device__ __forceinline__ void gemm_phase(PG8_LAS unsigned char* lds, const Gemm g, const Sched& S, const Epi& E) {
;     ...
;             PG8_LDB(B0, 1, 0); PG8_LDB(B1, 1, 1); PG8_SCHED; PG8_LDA(At, 1, 0); PG8_STAGE(PG8_SA(0, 1), a2 + hstepA, voffA);
;             PG8_WAIT_V(8); PG8_WAIT_L(0); PG8_BAR; PG8_MMA(0, 0, At, B0); PG8_MMA(0, 1, At, B1); PG8_BAR; PG8_SCHED;
;             PG8_LDA(At, 1, 1); PG8_STAGE(PG8_SB(1, 0), b3, voffB); PG8_STAGE(PG8_SB(1, 1), b3 + hstepB, voffB); PG8_STAGE(PG8_SA(1, 0), a3, voffA);
	s_setprio 1
	s_waitcnt lgkmcnt(0)
	v_mfma_f32_16x16x32_bf16 v[124:127], v[146:149], v[192:195], v[124:127]
	v_mfma_f32_16x16x32_bf16 v[120:123], v[166:169], v[192:195], v[120:123]
	v_mfma_f32_16x16x32_bf16 v[116:119], v[146:149], v[200:203], v[116:119]
	v_mfma_f32_16x16x32_bf16 v[112:115], v[166:169], v[200:203], v[112:115]
	v_mfma_f32_16x16x32_bf16 v[108:111], v[146:149], v[208:211], v[108:111]
	v_mfma_f32_16x16x32_bf16 v[104:107], v[166:169], v[208:211], v[104:107]
	v_mfma_f32_16x16x32_bf16 v[100:103], v[146:149], v[216:219], v[100:103]
	v_mfma_f32_16x16x32_bf16 v[96:99], v[166:169], v[216:219], v[96:99]
	v_mfma_f32_16x16x32_bf16 v[124:127], v[162:165], v[196:199], v[124:127]
	v_mfma_f32_16x16x32_bf16 v[120:123], v[170:173], v[196:199], v[120:123]
	v_mfma_f32_16x16x32_bf16 v[116:119], v[162:165], v[204:207], v[116:119]
	v_mfma_f32_16x16x32_bf16 v[112:115], v[170:173], v[204:207], v[112:115]
	v_mfma_f32_16x16x32_bf16 v[108:111], v[162:165], v[212:215], v[108:111]
	v_mfma_f32_16x16x32_bf16 v[104:107], v[170:173], v[212:215], v[104:107]
	v_mfma_f32_16x16x32_bf16 v[100:103], v[162:165], v[220:223], v[100:103]
	v_mfma_f32_16x16x32_bf16 v[96:99], v[170:173], v[220:223], v[96:99]
	s_setprio 0
	s_setprio 1
	v_mfma_f32_16x16x32_bf16 v[68:71], v[176:179], v[192:195], v[68:71]
	v_mfma_f32_16x16x32_bf16 v[64:67], v[184:187], v[192:195], v[64:67]
	v_mfma_f32_16x16x32_bf16 v[56:59], v[176:179], v[200:203], v[56:59]
	v_mfma_f32_16x16x32_bf16 v[48:51], v[184:187], v[200:203], v[48:51]
	v_mfma_f32_16x16x32_bf16 v[44:47], v[176:179], v[208:211], v[44:47]
	v_mfma_f32_16x16x32_bf16 v[40:43], v[184:187], v[208:211], v[40:43]
	v_mfma_f32_16x16x32_bf16 v[36:39], v[176:179], v[216:219], v[36:39]
	v_mfma_f32_16x16x32_bf16 v[32:35], v[184:187], v[216:219], v[32:35]
	v_mfma_f32_16x16x32_bf16 v[68:71], v[180:183], v[196:199], v[68:71]
	v_mfma_f32_16x16x32_bf16 v[64:67], v[188:191], v[196:199], v[64:67]
	v_mfma_f32_16x16x32_bf16 v[56:59], v[180:183], v[204:207], v[56:59]
	v_mfma_f32_16x16x32_bf16 v[48:51], v[188:191], v[204:207], v[48:51]
	v_mfma_f32_16x16x32_bf16 v[44:47], v[180:183], v[212:215], v[44:47]
	v_mfma_f32_16x16x32_bf16 v[40:43], v[188:191], v[212:215], v[40:43]
	v_mfma_f32_16x16x32_bf16 v[36:39], v[180:183], v[220:223], v[36:39]
	v_mfma_f32_16x16x32_bf16 v[32:35], v[188:191], v[220:223], v[32:35]
	s_setprio 0
	s_add_i32 s75, s75, s27
	v_lshl_add_u64 v[224:225], v[224:225], 0, s[8:9]
	s_mov_b32 m0, s75
	ds_read_b128 v[192:195], v161 offset:49152
	ds_read_b128 v[196:199], v161 offset:50176
	ds_read_b128 v[200:203], v161 offset:51200
	ds_read_b128 v[204:207], v161 offset:52224
	ds_read_b128 v[208:211], v161 offset:53248
	ds_read_b128 v[212:215], v161 offset:54272
	ds_read_b128 v[216:219], v161 offset:55296
	ds_read_b128 v[220:223], v161 offset:56320
	global_load_lds_dwordx4 v[224:225], off
	s_add_i32 m0, s75, 0x2000
	s_add_u32 s66, s66, 0x40080
	v_lshl_add_u64 v[224:225], v[226:227], 0, s[8:9]
	s_addc_u32 s67, s67, 0
	s_add_i32 s33, s33, s27
	global_load_lds_dwordx4 v[224:225], off
	v_lshl_add_u64 v[224:225], s[66:67], 0, v[132:133]
	s_mov_b32 m0, s33
	s_nop 0
	global_load_lds_dwordx4 v[224:225], off
	v_lshl_add_u64 v[224:225], s[66:67], 0, v[128:129]
	s_add_i32 m0, s33, 0x2000
	s_nop 0
	global_load_lds_dwordx4 v[224:225], off
	v_lshl_add_u64 v[224:225], v[228:229], 0, s[8:9]
	s_mov_b32 m0, s91
	s_nop 0
	global_load_lds_dwordx4 v[224:225], off
	v_lshl_add_u64 v[224:225], v[230:231], 0, s[8:9]
	s_mov_b32 m0, s92
	s_nop 0
	global_load_lds_dwordx4 v[224:225], off
	s_waitcnt vmcnt(8)
	s_waitcnt lgkmcnt(0)
	s_barrier
; #define PG8_STAGE(bufoff, gbase, voff) do { _Pragma("unroll") for (int _i = 0; _i < 2; ++_i) \
;         __builtin_amdgcn_global_load_lds((const unsigned*)((const char*)(gbase) + (voff)[_i]), (PG8_LAS unsigned*)(lds + (bufoff) + ldsw + _i * 8192), 16, 0, 0); } while (0)
; #define PG8_LDA(dst, b, h) do { _Pragma("unroll") for (int m = 0; m < 4; ++m) _Pragma("unroll") for (int k = 0; k < 2; ++k) dst[m][k] = *(const PG8_LAS bf16x8*)(lds + PG8_SA(b, h) + aoff + m * 2048 + k * 1024); } while (0)
; #define PG8_MMA(ai, bj, At, Bt) do { __builtin_amdgcn_s_setprio(1); _Pragma("unroll") for (int m = 0; m < 4; ++m) _Pragma("unroll") for (int n = 0; n < 2; ++n) _Pragma("unroll") for (int k = 0; k < 2; ++k) \
;         acc[ai][bj][m][n] = __builtin_amdgcn_mfma_f32_16x16x32_bf16(Bt[n][k], At[m][k], acc[ai][bj][m][n], 0, 0, 0); __builtin_amdgcn_s_setprio(0); } while (0)
; #define PG8_WAIT_V(n) asm volatile("s_waitcnt vmcnt(" #n ")" ::: "memory")
; #define PG8_WAIT_L(n) asm volatile("s_waitcnt lgkmcnt(" #n ")" ::: "memory")
; #define PG8_BAR __builtin_amdgcn_s_barrier()
; #define PG8_SCHED __builtin_amdgcn_sched_barrier(0)
; template <class Epi, class Sched, bool ALIGN_EPI = false, bool SP2 = false>
; __device__ __forceinline__ void gemm_phase(PG8_LAS unsigned char* lds, const Gemm g, const Sched& S, const Epi& E) {
;     ...
;             PG8_WAIT_V(8); PG8_WAIT_L(0); PG8_BAR; PG8_MMA(0, 0, At, B0); PG8_MMA(0, 1, At, B1); PG8_BAR; PG8_SCHED;
;             PG8_LDA(At, 1, 1); PG8_STAGE(PG8_SB(1, 0), b3, voffB); PG8_STAGE(PG8_SB(1, 1), b3 + hstepB, voffB); PG8_STAGE(PG8_SA(1, 0), a3, voffA);
;             PG8_WAIT_V(8); PG8_WAIT_L(0); PG8_BAR; PG8_MMA(1, 0, At, B0); PG8_MMA(1, 1, At, B1); PG8_BAR; PG8_SCHED;
;     ...
;         for (int a = 0; a < 2; ++a)
; #pragma unroll
;             for (int b = 0; b < 2; ++b)
; #pragma unroll
;                 for (int m = 0; m < 4; ++m)
; #pragma unroll
;                     for (int n = 0; n < 2; ++n) acc[a][b][m][n] = (f32x4){0.f, 0.f, 0.f, 0.f};
	s_setprio 1
	s_waitcnt lgkmcnt(0)
	v_mfma_f32_16x16x32_bf16 v[92:95], v[146:149], v[192:195], v[92:95]
	v_mfma_f32_16x16x32_bf16 v[88:91], v[166:169], v[192:195], v[88:91]
	v_mfma_f32_16x16x32_bf16 v[84:87], v[146:149], v[200:203], v[84:87]
	v_mfma_f32_16x16x32_bf16 v[80:83], v[166:169], v[200:203], v[80:83]
	v_mfma_f32_16x16x32_bf16 v[76:79], v[146:149], v[208:211], v[76:79]
	v_mfma_f32_16x16x32_bf16 v[72:75], v[166:169], v[208:211], v[72:75]
	v_mfma_f32_16x16x32_bf16 v[60:63], v[146:149], v[216:219], v[60:63]
	v_mfma_f32_16x16x32_bf16 v[52:55], v[166:169], v[216:219], v[52:55]
	v_mfma_f32_16x16x32_bf16 v[92:95], v[162:165], v[196:199], v[92:95]
	v_mfma_f32_16x16x32_bf16 v[88:91], v[170:173], v[196:199], v[88:91]
	v_mfma_f32_16x16x32_bf16 v[84:87], v[162:165], v[204:207], v[84:87]
	v_mfma_f32_16x16x32_bf16 v[80:83], v[170:173], v[204:207], v[80:83]
	v_mfma_f32_16x16x32_bf16 v[76:79], v[162:165], v[212:215], v[76:79]
	v_mfma_f32_16x16x32_bf16 v[72:75], v[170:173], v[212:215], v[72:75]
	v_mfma_f32_16x16x32_bf16 v[60:63], v[162:165], v[220:223], v[60:63]
	v_mfma_f32_16x16x32_bf16 v[52:55], v[170:173], v[220:223], v[52:55]
	s_setprio 0
	s_setprio 1
	v_mfma_f32_16x16x32_bf16 v[28:31], v[176:179], v[192:195], v[28:31]
	v_mfma_f32_16x16x32_bf16 v[24:27], v[184:187], v[192:195], v[24:27]
	v_mfma_f32_16x16x32_bf16 v[20:23], v[176:179], v[200:203], v[20:23]
	v_mfma_f32_16x16x32_bf16 v[16:19], v[184:187], v[200:203], v[16:19]
	v_mfma_f32_16x16x32_bf16 v[12:15], v[176:179], v[208:211], v[12:15]
	v_mfma_f32_16x16x32_bf16 v[8:11], v[184:187], v[208:211], v[8:11]
	v_mfma_f32_16x16x32_bf16 v[4:7], v[176:179], v[216:219], v[4:7]
	v_mfma_f32_16x16x32_bf16 v[0:3], v[184:187], v[216:219], v[0:3]
	v_mfma_f32_16x16x32_bf16 v[28:31], v[180:183], v[196:199], v[28:31]
	v_mfma_f32_16x16x32_bf16 v[24:27], v[188:191], v[196:199], v[24:27]
	v_mfma_f32_16x16x32_bf16 v[20:23], v[180:183], v[204:207], v[20:23]
	v_mfma_f32_16x16x32_bf16 v[16:19], v[188:191], v[204:207], v[16:19]
	v_mfma_f32_16x16x32_bf16 v[12:15], v[180:183], v[212:215], v[12:15]
	v_mfma_f32_16x16x32_bf16 v[8:11], v[188:191], v[212:215], v[8:11]
	v_mfma_f32_16x16x32_bf16 v[4:7], v[180:183], v[220:223], v[4:7]
	v_mfma_f32_16x16x32_bf16 v[0:3], v[188:191], v[220:223], v[0:3]
	s_setprio 0
	s_add_i32 s74, s74, 2
	s_add_u32 s60, s60, 0x100
	s_addc_u32 s61, s61, 0
	s_add_u32 s80, s80, 0x100
	s_addc_u32 s81, s81, 0
	s_cmp_gt_u32 s74, 13
	s_cbranch_scc0 .Lcopy_loop
	s_waitcnt vmcnt(0)
	s_barrier
	v_readlane_b32 s60, v237, 0
	v_readlane_b32 s61, v237, 1
	v_readlane_b32 s66, v237, 2
	v_readlane_b32 s67, v237, 3
	v_readlane_b32 s15, v237, 4
	v_readlane_b32 vcc_lo, v237, 5
	v_readlane_b32 s13, v237, 6
	v_readlane_b32 vcc_hi, v237, 7
	v_readlane_b32 s80, v237, 8
	v_readlane_b32 s81, v237, 9
	s_mov_b32 s74, -2
	v_mov_b32_e32 v0, 0
	v_mov_b32_e32 v1, v0
	v_mov_b32_e32 v2, v0
	v_mov_b32_e32 v3, v0
	v_mov_b32_e32 v4, v0
	v_mov_b32_e32 v5, v0
	v_mov_b32_e32 v6, v0
	v_mov_b32_e32 v7, v0
	v_mov_b32_e32 v8, v0
	v_mov_b32_e32 v9, v0
	v_mov_b32_e32 v10, v0
	v_mov_b32_e32 v11, v0
	v_mov_b32_e32 v12, v0
	v_mov_b32_e32 v13, v0
	v_mov_b32_e32 v14, v0
	v_mov_b32_e32 v15, v0
	v_mov_b32_e32 v16, v0
	v_mov_b32_e32 v17, v0
	v_mov_b32_e32 v18, v0
	v_mov_b32_e32 v19, v0
	v_mov_b32_e32 v20, v0
	v_mov_b32_e32 v21, v0
	v_mov_b32_e32 v22, v0
	v_mov_b32_e32 v23, v0
	v_mov_b32_e32 v24, v0
	v_mov_b32_e32 v25, v0
	v_mov_b32_e32 v26, v0
	v_mov_b32_e32 v27, v0
	v_mov_b32_e32 v28, v0
	v_mov_b32_e32 v29, v0
	v_mov_b32_e32 v30, v0
	v_mov_b32_e32 v31, v0
	v_mov_b32_e32 v52, v0
	v_mov_b32_e32 v53, v0
	v_mov_b32_e32 v54, v0
	v_mov_b32_e32 v55, v0
	v_mov_b32_e32 v60, v0
	v_mov_b32_e32 v61, v0
	v_mov_b32_e32 v62, v0
	v_mov_b32_e32 v63, v0
	v_mov_b32_e32 v72, v0
	v_mov_b32_e32 v73, v0
	v_mov_b32_e32 v74, v0
	v_mov_b32_e32 v75, v0
	v_mov_b32_e32 v76, v0
	v_mov_b32_e32 v77, v0
	v_mov_b32_e32 v78, v0
	v_mov_b32_e32 v79, v0
	v_mov_b32_e32 v80, v0
	v_mov_b32_e32 v81, v0
	v_mov_b32_e32 v82, v0
	v_mov_b32_e32 v83, v0
	v_mov_b32_e32 v84, v0
	v_mov_b32_e32 v85, v0
	v_mov_b32_e32 v86, v0
	v_mov_b32_e32 v87, v0
	v_mov_b32_e32 v88, v0
	v_mov_b32_e32 v89, v0
	v_mov_b32_e32 v90, v0
	v_mov_b32_e32 v91, v0
	v_mov_b32_e32 v92, v0
	v_mov_b32_e32 v93, v0
	v_mov_b32_e32 v94, v0
	v_mov_b32_e32 v95, v0
	v_mov_b32_e32 v32, v0
	v_mov_b32_e32 v33, v0
	v_mov_b32_e32 v34, v0
	v_mov_b32_e32 v35, v0
	v_mov_b32_e32 v36, v0
	v_mov_b32_e32 v37, v0
	v_mov_b32_e32 v38, v0
	v_mov_b32_e32 v39, v0
	v_mov_b32_e32 v40, v0
	v_mov_b32_e32 v41, v0
	v_mov_b32_e32 v42, v0
	v_mov_b32_e32 v43, v0
	v_mov_b32_e32 v44, v0
	v_mov_b32_e32 v45, v0
	v_mov_b32_e32 v46, v0
	v_mov_b32_e32 v47, v0
	v_mov_b32_e32 v48, v0
	v_mov_b32_e32 v49, v0
	v_mov_b32_e32 v50, v0
	v_mov_b32_e32 v51, v0
	v_mov_b32_e32 v56, v0
	v_mov_b32_e32 v57, v0
	v_mov_b32_e32 v58, v0
	v_mov_b32_e32 v59, v0
	v_mov_b32_e32 v64, v0
	v_mov_b32_e32 v65, v0
	v_mov_b32_e32 v66, v0
	v_mov_b32_e32 v67, v0
	v_mov_b32_e32 v68, v0
	v_mov_b32_e32 v69, v0
	v_mov_b32_e32 v70, v0
	v_mov_b32_e32 v71, v0
	v_mov_b32_e32 v96, v0
	v_mov_b32_e32 v97, v0
	v_mov_b32_e32 v98, v0
	v_mov_b32_e32 v99, v0
	v_mov_b32_e32 v100, v0
	v_mov_b32_e32 v101, v0
	v_mov_b32_e32 v102, v0
	v_mov_b32_e32 v103, v0
	v_mov_b32_e32 v104, v0
	v_mov_b32_e32 v105, v0
	v_mov_b32_e32 v106, v0
	v_mov_b32_e32 v107, v0
	v_mov_b32_e32 v108, v0
	v_mov_b32_e32 v109, v0
	v_mov_b32_e32 v110, v0
	v_mov_b32_e32 v111, v0
	v_mov_b32_e32 v112, v0
	v_mov_b32_e32 v113, v0
	v_mov_b32_e32 v114, v0
	v_mov_b32_e32 v115, v0
	v_mov_b32_e32 v116, v0
	v_mov_b32_e32 v117, v0
	v_mov_b32_e32 v118, v0
	v_mov_b32_e32 v119, v0
	v_mov_b32_e32 v120, v0
	v_mov_b32_e32 v121, v0
	v_mov_b32_e32 v122, v0
	v_mov_b32_e32 v123, v0
	v_mov_b32_e32 v124, v0
	v_mov_b32_e32 v125, v0
	v_mov_b32_e32 v126, v0
	v_mov_b32_e32 v127, v0
	s_nop 4
